# strategy 4: one static s_setprio 1 for the younger wave half (waves 4-7) in NA attention items, per-segment priority flips removed there
# baseline (speedup 1.0000x reference)
; __device__ __forceinline__ unsigned pk_bf16(float lo, float hi) { unsigned r; asm volatile("v_cvt_pk_bf16_f32 %0, %1, %2" : "=v"(r) : "v"(lo), "v"(hi)); return r; }
; __device__ __forceinline__ float xsum16(float v) { const auto r = __builtin_amdgcn_permlane16_swap(__float_as_uint(v), __float_as_uint(v), false, false); return __uint_as_float(r[0]) + __uint_as_float(r[1]); }
; __device__ __forceinline__ float xsum32(float v) { const auto r = __builtin_amdgcn_permlane32_swap(__float_as_uint(v), __float_as_uint(v), false, false); return __uint_as_float(r[0]) + __uint_as_float(r[1]); }
; __device__ __forceinline__ void na_item(int wv, const Params& p, int l, int it, LAS unsigned char* lds) {
;     ...
;     l_run = xsum16(l_run); l_run = xsum32(l_run);
;     const float inv = 1.0f / l_run;
; #pragma unroll
;     for (int d = 0; d < 4; ++d) { u32x2 w; w.x = pk_bf16(O[d][0] * inv, O[d][1] * inv); w.y = pk_bf16(O[d][2] * inv, O[d][3] * inv);
;         *(u32x2*)(Y + (size_t)qrow * 1024 + 256 + h * 64 + d * 16 + fq * 4) = w; }
.LBB0_665:
	s_setprio 0
	v_mov_b32_e32 v0, v189
	s_nop 1
	v_permlane16_swap_b32_e32 v189, v0
	v_add_f32_e32 v0, v189, v0
	v_mov_b32_e32 v2, v0
	s_nop 1
	v_permlane32_swap_b32_e32 v0, v2
	v_add_f32_e32 v0, v0, v2
	v_div_scale_f32 v2, s[4:5], v0, v0, 1.0
	v_rcp_f32_e32 v3, v2
	v_mov_b32_e32 v107, v1
	s_mov_b64 s[4:5], 0x800200
	v_readlane_b32 s96, v255, 3
	v_fma_f32 v4, -v2, v3, 1.0
	v_fmac_f32_e32 v3, v4, v3
	v_div_scale_f32 v4, vcc, 1.0, v0, 1.0
	v_mul_f32_e32 v5, v4, v3
	v_fma_f32 v6, -v2, v5, v4
	v_fmac_f32_e32 v5, v6, v3
	v_fma_f32 v2, -v2, v5, v4
	v_div_fmas_f32 v2, v2, v3, v5
	v_div_fixup_f32 v0, v2, v0, 1.0
	v_lshlrev_b64 v[2:3], 11, v[102:103]
	v_lshl_add_u64 v[2:3], s[92:93], 0, v[2:3]
	v_lshl_add_u64 v[2:3], s[78:79], 1, v[2:3]
	v_lshl_add_u64 v[2:3], v[106:107], 1, v[2:3]
	v_lshl_add_u64 v[4:5], v[2:3], 0, s[4:5]
	v_mul_f32_e32 v6, v68, v0
	v_mul_f32_e32 v7, v69, v0
	v_add_co_u32_e32 v2, vcc, s68, v2
	v_cvt_pk_bf16_f32 v6, v6, v7
	v_mul_f32_e32 v7, v70, v0
	s_nop 0
	v_addc_co_u32_e32 v3, vcc, 0, v3, vcc
	v_mul_f32_e32 v8, v71, v0
	v_cvt_pk_bf16_f32 v7, v7, v8
	global_store_dwordx2 v[2:3], v[6:7], off offset:512
	v_mul_f32_e32 v2, v80, v0
	v_mul_f32_e32 v3, v81, v0
	v_cvt_pk_bf16_f32 v2, v2, v3
	v_mul_f32_e32 v3, v82, v0
	v_mul_f32_e32 v6, v83, v0
	v_cvt_pk_bf16_f32 v3, v3, v6
	global_store_dwordx2 v[4:5], v[2:3], off offset:32
	v_mul_f32_e32 v2, v72, v0
	v_mul_f32_e32 v3, v73, v0
	v_cvt_pk_bf16_f32 v2, v2, v3
	v_mul_f32_e32 v3, v74, v0
	v_mul_f32_e32 v6, v75, v0
	v_cvt_pk_bf16_f32 v3, v3, v6
	global_store_dwordx2 v[4:5], v[2:3], off offset:64
	v_mul_f32_e32 v2, v76, v0
	v_mul_f32_e32 v3, v77, v0
	v_readlane_b32 s90, v255, 5
	v_readlane_b32 s92, v255, 8
	v_readlane_b32 s78, v255, 14
	v_cvt_pk_bf16_f32 v2, v2, v3
	v_mul_f32_e32 v3, v78, v0
	v_readlane_b32 s97, v255, 4
	v_readlane_b32 s91, v255, 6
	v_readlane_b32 s89, v255, 7
	v_readlane_b32 s93, v255, 9
	v_readlane_b32 s79, v255, 15
	s_movk_i32 s82, 0x1000
	s_movk_i32 s84, 0x2000
	s_movk_i32 s88, 0x3000
	s_movk_i32 s63, 0x5000
	v_readlane_b32 s76, v255, 16
	s_mov_b32 s77, 0x2aaaaaab
	s_movk_i32 s86, 0xc40
	v_readlane_b32 s87, v255, 17
	v_readlane_b32 s72, v255, 22
	v_mul_f32_e32 v0, v79, v0
	v_cvt_pk_bf16_f32 v3, v3, v0
	global_store_dwordx2 v[4:5], v[2:3], off offset:96
	v_readlane_b32 s73, v255, 23

; __device__ __forceinline__ void na_item(int wv, const Params& p, int l, int it, LAS unsigned char* lds) {
;     ...
;         if (lat) {
;             const int p0 = 5 * ps, lo = max(off, p0), hi = min(off + 8, ps ? 9 : 5);
;             int rel = lo;
;             for (; rel + 1 < hi; rel += 2) { const int key0[2] = {(rel - p0) * 64 + cst, (rel + 1 - p0) * 64 + cst}; const int dr[2] = {(r0 + rel - off) - r + 7, (r0 + rel + 1 - off) - r + 7};
;                 na_step<2>(lds, NB_KLOC, NB_VLOC, 656, key0, true, dr, rpb, qf, fr, fq, lane, cst, cq, c0w, m_run, l_run, O); }
.LBB0_712:
	s_bitcmp1_b32 s23, 8
	s_cbranch_scc0 .Lna_prio_skip
	s_setprio 1

; #define LAS __attribute__((address_space(3)))
; __device__ __forceinline__ unsigned pk_bf16(float lo, float hi) { unsigned r; asm volatile("v_cvt_pk_bf16_f32 %0, %1, %2" : "=v"(r) : "v"(lo), "v"(hi)); return r; }
; __device__ __forceinline__ f32x4 mfma16(bf16x8 a, bf16x8 b, f32x4 c) { return __builtin_amdgcn_mfma_f32_16x16x32_bf16(a, b, c, 0, 0, 0); }
; template <int ND> ...
;     f32x4 sc[2 * ND];
; #pragma unroll
;     for (int u = 0; u < 2 * ND; ++u) sc[u] = (f32x4){0.f, 0.f, 0.f, 0.f};
;     __builtin_amdgcn_s_setprio(1);
; #pragma unroll
;     for (int kk = 0; kk < 2; ++kk)
; #pragma unroll
;         for (int u = 0; u < 2 * ND; ++u) {
;             const bf16x8 kf = *(const LAS bf16x8*)(lds + kbase + (key0[u >> 1] + (u & 1) * 16 + fr) * 144 + kk * 64 + fq * 16);
;             sc[u] = mfma16(kf, qf[kk], sc[u]); }
;     __builtin_amdgcn_s_setprio(0);
;     if (loc) {
; #pragma unroll
;         for (int g = 0; g < ND; ++g)
; #pragma unroll
;             for (int i = 0; i < 4; ++i) {
;                 const int ck0 = cst + fq * 4 + i, ck1 = ck0 + 16;
;                 const int rel0 = min(max(ck0 - cq + 15, 0), 30), rel1 = min(max(ck1 - cq + 15, 0), 30);
;                 const bool v0 = (ck0 >= c0w) && (ck0 < c0w + 16), v1 = (ck1 >= c0w) && (ck1 < c0w + 16);
;                 sc[2 * g][i] = v0 ? sc[2 * g][i] + rpb[dr[g] * 31 + rel0] : -INFINITY;
;                 sc[2 * g + 1][i] = v1 ? sc[2 * g + 1][i] + rpb[dr[g] * 31 + rel1] : -INFINITY; }
;     }
;     float mx = -INFINITY;
; #pragma unroll
;     for (int u = 0; u < 2 * ND; ++u) mx = fmaxf(mx, fmaxf(fmaxf(sc[u][0], sc[u][1]), fmaxf(sc[u][2], sc[u][3])));
;     mx = xmax16(mx); mx = xmax32(mx);
;     const float m_new = fmaxf(m_run, mx);
;     const float m_use = (m_new == -INFINITY) ? 0.f : m_new;
;     const float alpha = __builtin_amdgcn_exp2f(m_run - m_use);
;     float ps_sum = 0.f; bf16x8 pf[ND];
; #pragma unroll
;     for (int g = 0; g < ND; ++g) { float pv[8];
; #pragma unroll
;         for (int i = 0; i < 4; ++i) { pv[i] = __builtin_amdgcn_exp2f(sc[2 * g][i] - m_use); pv[4 + i] = __builtin_amdgcn_exp2f(sc[2 * g + 1][i] - m_use); ps_sum += pv[i] + pv[4 + i]; }
;         u32x4 pw; pw.x = pk_bf16(pv[0], pv[1]); pw.y = pk_bf16(pv[2], pv[3]); pw.z = pk_bf16(pv[4], pv[5]); pw.w = pk_bf16(pv[6], pv[7]);
;         pf[g] = as_bf8(pw); }
.LBB0_737:
	v_add_u32_e32 v234, v159, v105
	ds_read2_b64 v[220:223], v234 offset1:4
	ds_read2_b64 v[224:227], v187 offset1:4
	v_add_u32_e32 v235, 0x2000, v234
	ds_read2_b64 v[248:251], v235 offset0:64 offset1:68
	ds_read_b128 v[84:87], v186
	ds_read_b128 v[210:213], v186 offset:64
	ds_read_b128 v[88:91], v186 offset:2304
	ds_read_b128 v[92:95], v186 offset:4608
	ds_read_b128 v[96:99], v186 offset:6912
	ds_read_b128 v[188:191], v186 offset:9216
	ds_read_b128 v[198:201], v186 offset:13824
	ds_read_b128 v[214:217], v186 offset:13888
	ds_read_b128 v[192:195], v186 offset:11520
	s_waitcnt lgkmcnt(8)
	v_mfma_f32_16x16x32_bf16 v[84:87], v[84:87], v[4:7], 0
	ds_read_b128 v[206:209], v186 offset:16128
	s_waitcnt lgkmcnt(8)
	v_mfma_f32_16x16x32_bf16 v[84:87], v[210:213], v[8:11], v[84:87]
	ds_read_b128 v[210:213], v186 offset:2368
	s_waitcnt lgkmcnt(8)
	v_mfma_f32_16x16x32_bf16 v[88:91], v[88:91], v[4:7], 0
	s_waitcnt lgkmcnt(4)
	v_mfma_f32_16x16x32_bf16 v[198:201], v[198:201], v[4:7], 0
	s_waitcnt lgkmcnt(0)
	v_mfma_f32_16x16x32_bf16 v[88:91], v[210:213], v[8:11], v[88:91]
	ds_read_b128 v[210:213], v186 offset:4672
	v_mfma_f32_16x16x32_bf16 v[92:95], v[92:95], v[4:7], 0
	s_waitcnt lgkmcnt(0)
	v_mfma_f32_16x16x32_bf16 v[92:95], v[210:213], v[8:11], v[92:95]
	ds_read_b128 v[210:213], v186 offset:6976
	v_mfma_f32_16x16x32_bf16 v[96:99], v[96:99], v[4:7], 0
	s_waitcnt lgkmcnt(0)
	v_mfma_f32_16x16x32_bf16 v[96:99], v[210:213], v[8:11], v[96:99]
	ds_read_b128 v[210:213], v186 offset:9280
	v_mfma_f32_16x16x32_bf16 v[188:191], v[188:191], v[4:7], 0
	s_waitcnt lgkmcnt(0)
	v_mfma_f32_16x16x32_bf16 v[210:213], v[210:213], v[8:11], v[188:191]
	s_nop 5
	ds_read_b128 v[188:191], v186 offset:11584
	v_mfma_f32_16x16x32_bf16 v[198:201], v[214:217], v[8:11], v[198:201]
	ds_read_b128 v[214:217], v186 offset:16192
	v_mfma_f32_16x16x32_bf16 v[192:195], v[192:195], v[4:7], 0
	v_mfma_f32_16x16x32_bf16 v[206:209], v[206:209], v[4:7], 0
	s_waitcnt lgkmcnt(1)
	v_mfma_f32_16x16x32_bf16 v[190:193], v[188:191], v[8:11], v[192:195]
	s_waitcnt lgkmcnt(0)
	v_mfma_f32_16x16x32_bf16 v[206:209], v[214:217], v[8:11], v[206:209]
	v_max_f32_e32 v0, v87, v87
	v_max_f32_e32 v188, v86, v86
	v_max_f32_e32 v0, v188, v0
	v_max_f32_e32 v188, v91, v91
	v_max_f32_e32 v189, v90, v90
	v_max_f32_e32 v188, v189, v188
	v_max3_f32 v0, v84, v85, v0
	v_max3_f32 v188, v88, v89, v188
	v_max3_f32 v0, v0, s71, v188
	v_max_f32_e32 v188, v95, v95
	v_max_f32_e32 v189, v94, v94
	v_max_f32_e32 v188, v189, v188
	v_max_f32_e32 v189, v99, v99
	v_max_f32_e32 v194, v98, v98
	v_max_f32_e32 v189, v194, v189
	v_max3_f32 v188, v92, v93, v188
	v_max3_f32 v189, v96, v97, v189
	v_max3_f32 v0, v0, v188, v189
	v_max_f32_e32 v188, v213, v213
	v_max_f32_e32 v189, v212, v212
	v_max_f32_e32 v188, v189, v188
	v_max_f32_e32 v189, v193, v193
	v_max_f32_e32 v194, v192, v192
	v_max_f32_e32 v189, v194, v189
	v_max3_f32 v188, v210, v211, v188
	v_max3_f32 v189, v190, v191, v189
	v_max3_f32 v0, v0, v188, v189
	v_max_f32_e32 v188, v201, v201
	v_max_f32_e32 v189, v200, v200
	v_max_f32_e32 v188, v189, v188
	v_max_f32_e32 v189, v209, v209
	v_max_f32_e32 v194, v208, v208
	v_max_f32_e32 v189, v194, v189
	v_max3_f32 v188, v198, v199, v188
	v_max3_f32 v189, v206, v207, v189
	v_max3_f32 v0, v0, v188, v189
	v_mov_b32_e32 v188, v0
	s_nop 1
	v_permlane16_swap_b32_e32 v0, v188
	v_max_f32_e32 v188, v188, v188
	v_max_f32_e32 v0, v0, v0
	v_max_f32_e32 v0, v0, v188
	v_mov_b32_e32 v188, v0
	s_nop 1
	v_permlane32_swap_b32_e32 v0, v188
	v_max3_f32 v188, v3, v0, v188
	v_cmp_neq_f32_e32 vcc, s71, v188
	s_nop 1
	v_cndmask_b32_e32 v0, 0, v188, vcc
	v_sub_f32_e32 v84, v84, v0
	v_sub_f32_e32 v88, v88, v0
	v_exp_f32_e32 v84, v84
	v_exp_f32_e32 v189, v88
	v_sub_f32_e32 v85, v85, v0
	v_sub_f32_e32 v88, v89, v0
	v_exp_f32_e32 v85, v85
	v_exp_f32_e32 v194, v88
	v_sub_f32_e32 v86, v86, v0
	v_sub_f32_e32 v90, v90, v0
	v_exp_f32_e32 v86, v86
	v_exp_f32_e32 v195, v90
	v_sub_f32_e32 v87, v87, v0
	v_sub_f32_e32 v90, v91, v0
	v_exp_f32_e32 v87, v87
	v_exp_f32_e32 v204, v90
	v_add_f32_e32 v88, v189, v84
	v_add_f32_e32 v88, 0, v88
	v_add_f32_e32 v89, v194, v85
	v_add_f32_e32 v88, v89, v88
	v_add_f32_e32 v89, v195, v86
	v_add_f32_e32 v88, v89, v88
	v_add_f32_e32 v89, v204, v87
	v_add_f32_e32 v89, v89, v88
	v_sub_f32_e32 v88, v92, v0
	v_exp_f32_e32 v205, v88
	v_sub_f32_e32 v88, v96, v0
	v_exp_f32_e32 v214, v88
	v_sub_f32_e32 v88, v93, v0
	v_sub_f32_e32 v90, v97, v0
	v_exp_f32_e32 v88, v88
	v_exp_f32_e32 v90, v90
	v_add_f32_e32 v91, v214, v205
	v_cvt_pk_bf16_f32 v84, v84, v85
	v_cvt_pk_bf16_f32 v85, v86, v87
	v_pk_add_f32 v[86:87], v[90:91], v[88:89]
	v_sub_f32_e32 v3, v3, v0
	v_pk_add_f32 v[92:93], v[86:87], v[86:87] op_sel_hi:[0,1]
	v_sub_f32_e32 v86, v94, v0
	v_exp_f32_e32 v89, v86
	v_sub_f32_e32 v86, v98, v0
	v_exp_f32_e32 v91, v86
	v_sub_f32_e32 v86, v95, v0
; #define LAS __attribute__((address_space(3)))
; __device__ __forceinline__ unsigned pk_bf16(float lo, float hi) { unsigned r; asm volatile("v_cvt_pk_bf16_f32 %0, %1, %2" : "=v"(r) : "v"(lo), "v"(hi)); return r; }
; __device__ __forceinline__ f32x4 mfma16(bf16x8 a, bf16x8 b, f32x4 c) { return __builtin_amdgcn_mfma_f32_16x16x32_bf16(a, b, c, 0, 0, 0); }
; template <int ND> ...
;     ...
;     for (int g = 0; g < ND; ++g) { float pv[8];
; #pragma unroll
;         for (int i = 0; i < 4; ++i) { pv[i] = __builtin_amdgcn_exp2f(sc[2 * g][i] - m_use); pv[4 + i] = __builtin_amdgcn_exp2f(sc[2 * g + 1][i] - m_use); ps_sum += pv[i] + pv[4 + i]; }
;         u32x4 pw; pw.x = pk_bf16(pv[0], pv[1]); pw.y = pk_bf16(pv[2], pv[3]); pw.z = pk_bf16(pv[4], pv[5]); pw.w = pk_bf16(pv[6], pv[7]);
;         pf[g] = as_bf8(pw); }
;     l_run = l_run * alpha + ps_sum; m_run = m_new;
;     __builtin_amdgcn_s_setprio(1);
; #pragma unroll
;     for (int d = 0; d < 4; ++d) { O[d] = O[d] * alpha;
; #pragma unroll
;         for (int g = 0; g < ND; ++g) {
;             const u32x2 va = *(const LAS u32x2*)(lds + vbase + (d * 16 + fr) * vstr + (key0[g] + fq * 4) * 2);
;             const u32x2 vb = *(const LAS u32x2*)(lds + vbase + (d * 16 + fr) * vstr + (key0[g] + 16 + fq * 4) * 2);
;             u32x4 vw; vw.x = va.x; vw.y = va.y; vw.z = vb.x; vw.w = vb.y;
;             O[d] = mfma16(as_bf8(vw), pf[g], O[d]); } }
;     __builtin_amdgcn_s_setprio(0);
	v_exp_f32_e32 v92, v86
	v_sub_f32_e32 v86, v99, v0
	v_exp_f32_e32 v94, v86
	v_add_f32_e32 v95, v91, v89
	v_cvt_pk_bf16_f32 v86, v189, v194
	v_cvt_pk_bf16_f32 v87, v195, v204
	v_pk_add_f32 v[96:97], v[94:95], v[92:93]
	v_sub_f32_e32 v93, v210, v0
	v_exp_f32_e32 v95, v93
	v_sub_f32_e32 v93, v190, v0
	v_pk_add_f32 v[96:97], v[96:97], v[96:97] op_sel_hi:[0,1]
	v_exp_f32_e32 v189, v93
	v_sub_f32_e32 v93, v211, v0
	v_exp_f32_e32 v96, v93
	v_sub_f32_e32 v93, v191, v0
	v_exp_f32_e32 v98, v93
	v_add_f32_e32 v99, v189, v95
	v_cvt_pk_bf16_f32 v88, v205, v88
	v_cvt_pk_bf16_f32 v89, v89, v92
	v_pk_add_f32 v[92:93], v[98:99], v[96:97]
	v_cvt_pk_bf16_f32 v90, v214, v90
	v_cvt_pk_bf16_f32 v91, v91, v94
	s_nop 0
	v_pk_add_f32 v[190:191], v[92:93], v[92:93] op_sel_hi:[0,1]
	v_sub_f32_e32 v92, v212, v0
	v_exp_f32_e32 v97, v92
	v_sub_f32_e32 v92, v192, v0
	v_exp_f32_e32 v99, v92
	v_sub_f32_e32 v92, v213, v0
	v_exp_f32_e32 v190, v92
	v_sub_f32_e32 v92, v193, v0
	v_exp_f32_e32 v192, v92
	v_add_f32_e32 v193, v99, v97
	v_pk_add_f32 v[92:93], v[192:193], v[190:191]
	s_nop 0
	v_pk_add_f32 v[194:195], v[92:93], v[92:93] op_sel_hi:[0,1]
	v_sub_f32_e32 v92, v198, v0
	v_exp_f32_e32 v193, v92
	v_sub_f32_e32 v92, v206, v0
	v_exp_f32_e32 v204, v92
	v_sub_f32_e32 v92, v199, v0
	v_exp_f32_e32 v194, v92
	v_sub_f32_e32 v92, v207, v0
	v_exp_f32_e32 v198, v92
	v_add_f32_e32 v199, v204, v193
	v_cvt_pk_bf16_f32 v92, v95, v96
	v_cvt_pk_bf16_f32 v93, v97, v190
	v_pk_add_f32 v[94:95], v[198:199], v[194:195]
	s_nop 0
	v_pk_add_f32 v[190:191], v[94:95], v[94:95] op_sel_hi:[0,1]
	v_sub_f32_e32 v94, v200, v0
	v_exp_f32_e32 v195, v94
	v_sub_f32_e32 v94, v208, v0
	v_exp_f32_e32 v199, v94
	v_sub_f32_e32 v94, v201, v0
	v_sub_f32_e32 v0, v209, v0
	v_exp_f32_e32 v190, v94
	v_exp_f32_e32 v200, v0
	v_exp_f32_e32 v0, v3
	v_add_f32_e32 v201, v199, v195
	v_cvt_pk_bf16_f32 v94, v189, v98
	v_pk_add_f32 v[96:97], v[200:201], v[190:191]
	v_cvt_pk_bf16_f32 v95, v99, v192
	s_nop 0
	v_add_f32_e32 v189, v96, v97
	v_fmac_f32_e32 v189, v2, v0
	v_cvt_pk_bf16_f32 v96, v193, v194
	v_cvt_pk_bf16_f32 v97, v195, v190
	v_cvt_pk_bf16_f32 v98, v204, v198
	v_cvt_pk_bf16_f32 v99, v199, v200
	v_add_u32_e32 v219, 0x3000, v234
	ds_read2_b64 v[190:193], v219 offset0:96 offset1:100
	ds_read2_b64 v[198:201], v234 offset0:8 offset1:12
	ds_read2_b64 v[206:209], v187 offset0:8 offset1:12
	ds_read2_b64 v[210:213], v235 offset0:72 offset1:76
	ds_read2_b64 v[214:217], v219 offset0:104 offset1:108
	v_pk_mul_f32 v[68:69], v[68:69], v[0:1] op_sel_hi:[1,0]
	v_pk_mul_f32 v[70:71], v[70:71], v[0:1] op_sel_hi:[1,0]
	v_pk_mul_f32 v[80:81], v[80:81], v[0:1] op_sel_hi:[1,0]
	v_pk_mul_f32 v[82:83], v[82:83], v[0:1] op_sel_hi:[1,0]
	v_pk_mul_f32 v[72:73], v[72:73], v[0:1] op_sel_hi:[1,0]
	v_pk_mul_f32 v[74:75], v[74:75], v[0:1] op_sel_hi:[1,0]
	v_pk_mul_f32 v[76:77], v[76:77], v[0:1] op_sel_hi:[1,0]
	v_pk_mul_f32 v[78:79], v[78:79], v[0:1] op_sel_hi:[1,0]
	s_waitcnt lgkmcnt(5)
	v_mfma_f32_16x16x32_bf16 v[68:71], v[220:223], v[84:87], v[68:71]
	v_mfma_f32_16x16x32_bf16 v[80:83], v[224:227], v[84:87], v[80:83]
	v_mfma_f32_16x16x32_bf16 v[72:75], v[248:251], v[84:87], v[72:75]
	ds_read2_b64 v[220:223], v234 offset0:16 offset1:20
	ds_read2_b64 v[224:227], v187 offset0:16 offset1:20
	ds_read2_b64 v[248:251], v235 offset0:80 offset1:84
	s_waitcnt lgkmcnt(7)
	v_mfma_f32_16x16x32_bf16 v[76:79], v[190:193], v[84:87], v[76:79]
	ds_read2_b64 v[190:193], v219 offset0:112 offset1:116
	s_waitcnt lgkmcnt(7)
	v_mfma_f32_16x16x32_bf16 v[68:71], v[198:201], v[88:91], v[68:71]
	ds_read2_b64 v[198:201], v234 offset0:24 offset1:28
	s_waitcnt lgkmcnt(7)
	v_mfma_f32_16x16x32_bf16 v[80:83], v[206:209], v[88:91], v[80:83]
	ds_read2_b64 v[206:209], v187 offset0:24 offset1:28
	s_waitcnt lgkmcnt(7)
	v_mfma_f32_16x16x32_bf16 v[72:75], v[210:213], v[88:91], v[72:75]
	ds_read2_b64 v[210:213], v235 offset0:88 offset1:92
	s_waitcnt lgkmcnt(7)
	v_mfma_f32_16x16x32_bf16 v[76:79], v[214:217], v[88:91], v[76:79]
	ds_read2_b64 v[214:217], v219 offset0:120 offset1:124
	s_waitcnt lgkmcnt(7)
	v_mfma_f32_16x16x32_bf16 v[68:71], v[220:223], v[92:95], v[68:71]
	s_waitcnt lgkmcnt(6)
	v_mfma_f32_16x16x32_bf16 v[80:83], v[224:227], v[92:95], v[80:83]
	s_waitcnt lgkmcnt(5)
	v_mfma_f32_16x16x32_bf16 v[72:75], v[248:251], v[92:95], v[72:75]
	s_waitcnt lgkmcnt(4)
	v_mfma_f32_16x16x32_bf16 v[76:79], v[190:193], v[92:95], v[76:79]
	s_waitcnt lgkmcnt(3)
	v_mfma_f32_16x16x32_bf16 v[68:71], v[198:201], v[96:99], v[68:71]
	s_waitcnt lgkmcnt(2)
	v_mfma_f32_16x16x32_bf16 v[80:83], v[206:209], v[96:99], v[80:83]
	s_waitcnt lgkmcnt(1)
	v_mfma_f32_16x16x32_bf16 v[72:75], v[210:213], v[96:99], v[72:75]
	s_waitcnt lgkmcnt(0)
	v_mfma_f32_16x16x32_bf16 v[76:79], v[214:217], v[96:99], v[76:79]
	s_mov_b32 s3, 5
	s_mov_b64 s[88:89], 0
	s_andn2_b64 vcc, exec, s[50:51]
	s_mov_b64 s[72:73], -1
	s_cbranch_vccz .LBB0_665

; #define LAS __attribute__((address_space(3)))
; __device__ __forceinline__ f32x4 mfma16(bf16x8 a, bf16x8 b, f32x4 c) { return __builtin_amdgcn_mfma_f32_16x16x32_bf16(a, b, c, 0, 0, 0); }
; template <int ND> ...
;     ...
;     __builtin_amdgcn_s_setprio(1);
; #pragma unroll
;     for (int kk = 0; kk < 2; ++kk)
; #pragma unroll
;         for (int u = 0; u < 2 * ND; ++u) {
;             const bf16x8 kf = *(const LAS bf16x8*)(lds + kbase + (key0[u >> 1] + (u & 1) * 16 + fr) * 144 + kk * 64 + fq * 16);
;             sc[u] = mfma16(kf, qf[kk], sc[u]); }
;     __builtin_amdgcn_s_setprio(0);
;     if (loc) {
; #pragma unroll
;         for (int g = 0; g < ND; ++g)
; #pragma unroll
;             for (int i = 0; i < 4; ++i) {
;                 const int ck0 = cst + fq * 4 + i, ck1 = ck0 + 16;
;                 const int rel0 = min(max(ck0 - cq + 15, 0), 30), rel1 = min(max(ck1 - cq + 15, 0), 30);
;                 const bool v0 = (ck0 >= c0w) && (ck0 < c0w + 16), v1 = (ck1 >= c0w) && (ck1 < c0w + 16);
;                 sc[2 * g][i] = v0 ? sc[2 * g][i] + rpb[dr[g] * 31 + rel0] : -INFINITY;
;                 sc[2 * g + 1][i] = v1 ? sc[2 * g + 1][i] + rpb[dr[g] * 31 + rel1] : -INFINITY; }
.LBB0_775:
	v_add_u32_e32 v2, v166, v191
	v_add_u32_e32 v0, v175, v210
	ds_read_b128 v[96:99], v0
	ds_read_b128 v[92:95], v2
	ds_read_b128 v[84:87], v2 offset:6912
	ds_read_b128 v[88:91], v2 offset:9216
	ds_read_b128 v[198:201], v0 offset:64
	ds_read_b128 v[212:215], v2 offset:64
	ds_read_b128 v[220:223], v2 offset:6976
	ds_read_b128 v[224:227], v2 offset:9280
	ds_read_b32 v3, v192
	ds_read_b32 v234, v193
	ds_read_b32 v235, v194
	ds_read_b32 v248, v195
	ds_read_b32 v249, v206
	ds_read_b32 v250, v207
	ds_read_b32 v251, v208
	s_waitcnt lgkmcnt(11)
	v_mfma_f32_16x16x32_bf16 v[96:99], v[96:99], v[4:7], 0
	v_mfma_f32_16x16x32_bf16 v[92:95], v[92:95], v[4:7], 0
	v_mfma_f32_16x16x32_bf16 v[84:87], v[84:87], v[4:7], 0
	v_mfma_f32_16x16x32_bf16 v[88:91], v[88:91], v[4:7], 0
	ds_read_b32 v219, v209
	s_waitcnt lgkmcnt(10)
	v_mfma_f32_16x16x32_bf16 v[96:99], v[198:201], v[8:11], v[96:99]
	v_mfma_f32_16x16x32_bf16 v[92:95], v[212:215], v[8:11], v[92:95]
	ds_read_b32 v198, v192 offset:124
	ds_read_b32 v199, v193 offset:124
	ds_read_b32 v200, v194 offset:124
	ds_read_b32 v201, v195 offset:124
	ds_read_b32 v212, v206 offset:124
	s_waitcnt lgkmcnt(13)
	v_mfma_f32_16x16x32_bf16 v[84:87], v[220:223], v[8:11], v[84:87]
	v_mfma_f32_16x16x32_bf16 v[88:91], v[224:227], v[8:11], v[88:91]
	s_waitcnt lgkmcnt(5)
	ds_read_b32 v213, v207 offset:124
	ds_read_b32 v214, v208 offset:124
	ds_read_b32 v215, v209 offset:124
	v_mov_b32_e32 v216, 0xff800000
	v_add_f32_e32 v3, v96, v3
	v_cndmask_b32_e64 v2, v216, v3, s[64:65]
	v_add_f32_e32 v234, v92, v234
	v_cndmask_b32_e64 v0, v216, v234, s[90:91]
	v_add_f32_e32 v235, v97, v235
	v_cndmask_b32_e64 v96, v216, v235, s[74:75]
	v_add_f32_e32 v248, v93, v248
	v_cndmask_b32_e64 v92, v216, v248, s[96:97]
	v_add_f32_e32 v249, v98, v249
	v_cndmask_b32_e64 v97, v216, v249, s[8:9]
	v_add_f32_e32 v250, v94, v250
	v_cndmask_b32_e64 v93, v216, v250, s[86:87]
	v_add_f32_e32 v251, v99, v251
	v_cndmask_b32_e64 v98, v216, v251, s[60:61]
	v_add_f32_e32 v219, v95, v219
	v_cndmask_b32_e64 v94, v216, v219, s[52:53]
	s_waitcnt lgkmcnt(0)
; #define LAS __attribute__((address_space(3)))
; __device__ __forceinline__ unsigned pk_bf16(float lo, float hi) { unsigned r; asm volatile("v_cvt_pk_bf16_f32 %0, %1, %2" : "=v"(r) : "v"(lo), "v"(hi)); return r; }
; __device__ __forceinline__ f32x4 mfma16(bf16x8 a, bf16x8 b, f32x4 c) { return __builtin_amdgcn_mfma_f32_16x16x32_bf16(a, b, c, 0, 0, 0); }
; __device__ __forceinline__ float xmax16(float v) { const auto r = __builtin_amdgcn_permlane16_swap(__float_as_uint(v), __float_as_uint(v), false, false); return fmaxf(__uint_as_float(r[0]), __uint_as_float(r[1])); }
; __device__ __forceinline__ float xmax32(float v) { const auto r = __builtin_amdgcn_permlane32_swap(__float_as_uint(v), __float_as_uint(v), false, false); return fmaxf(__uint_as_float(r[0]), __uint_as_float(r[1])); }
; template <int ND> ...
;     ...
;     float mx = -INFINITY;
; #pragma unroll
;     for (int u = 0; u < 2 * ND; ++u) mx = fmaxf(mx, fmaxf(fmaxf(sc[u][0], sc[u][1]), fmaxf(sc[u][2], sc[u][3])));
;     mx = xmax16(mx); mx = xmax32(mx);
;     const float m_new = fmaxf(m_run, mx);
;     const float m_use = (m_new == -INFINITY) ? 0.f : m_new;
;     const float alpha = __builtin_amdgcn_exp2f(m_run - m_use);
;     float ps_sum = 0.f; bf16x8 pf[ND];
; #pragma unroll
;     for (int g = 0; g < ND; ++g) { float pv[8];
; #pragma unroll
;         for (int i = 0; i < 4; ++i) { pv[i] = __builtin_amdgcn_exp2f(sc[2 * g][i] - m_use); pv[4 + i] = __builtin_amdgcn_exp2f(sc[2 * g + 1][i] - m_use); ps_sum += pv[i] + pv[4 + i]; }
;         u32x4 pw; pw.x = pk_bf16(pv[0], pv[1]); pw.y = pk_bf16(pv[2], pv[3]); pw.z = pk_bf16(pv[4], pv[5]); pw.w = pk_bf16(pv[6], pv[7]);
;         pf[g] = as_bf8(pw); }
;     l_run = l_run * alpha + ps_sum; m_run = m_new;
;     __builtin_amdgcn_s_setprio(1);
; #pragma unroll
;     for (int d = 0; d < 4; ++d) { O[d] = O[d] * alpha;
; #pragma unroll
;         for (int g = 0; g < ND; ++g) {
;             const u32x2 va = *(const LAS u32x2*)(lds + vbase + (d * 16 + fr) * vstr + (key0[g] + fq * 4) * 2);
;             const u32x2 vb = *(const LAS u32x2*)(lds + vbase + (d * 16 + fr) * vstr + (key0[g] + 16 + fq * 4) * 2);
;             u32x4 vw; vw.x = va.x; vw.y = va.y; vw.z = vb.x; vw.w = vb.y;
;             O[d] = mfma16(as_bf8(vw), pf[g], O[d]); } }
;     __builtin_amdgcn_s_setprio(0);
	v_add_f32_e32 v198, v84, v198
	v_cndmask_b32_e64 v99, v216, v198, s[64:65]
	v_add_f32_e32 v199, v88, v199
	v_cndmask_b32_e64 v95, v216, v199, s[90:91]
	v_add_f32_e32 v200, v85, v200
	v_cndmask_b32_e64 v88, v216, v200, s[74:75]
	v_add_f32_e32 v201, v89, v201
	v_cndmask_b32_e64 v84, v216, v201, s[96:97]
	v_add_f32_e32 v212, v86, v212
	v_cndmask_b32_e64 v212, v216, v212, s[8:9]
	v_add_f32_e32 v213, v90, v213
	v_cndmask_b32_e64 v85, v216, v213, s[86:87]
	v_add_f32_e32 v214, v87, v214
	v_cndmask_b32_e64 v90, v216, v214, s[60:61]
	v_add_f32_e32 v215, v91, v215
	v_cndmask_b32_e64 v86, v216, v215, s[52:53]
	v_add_u32_e32 v219, 0xb000, v190
	v_add_u32_e32 v234, 0xd800, v190
	v_add_u32_e32 v235, 0x10600, v190
	ds_read2_b64 v[220:223], v219 offset0:128 offset1:132
	ds_read2_b64 v[224:227], v234 offset0:160 offset1:164
	ds_read2_b64 v[248:251], v235 offset1:4
	v_max_f32_e32 v3, v98, v98
	v_max_f32_e32 v87, v97, v97
	v_max_f32_e32 v3, v87, v3
	v_max_f32_e32 v87, v94, v94
	v_max_f32_e32 v89, v93, v93
	v_max_f32_e32 v87, v89, v87
	v_max3_f32 v3, v2, v96, v3
	v_max3_f32 v87, v0, v92, v87
	v_max3_f32 v3, v3, s71, v87
	v_max_f32_e32 v87, v90, v90
	v_max_f32_e32 v89, v212, v212
	v_max_f32_e32 v87, v89, v87
	v_max_f32_e32 v89, v86, v86
	v_max_f32_e32 v91, v85, v85
	v_max_f32_e32 v89, v91, v89
	v_max3_f32 v87, v99, v88, v87
	v_max3_f32 v89, v95, v84, v89
	v_max3_f32 v3, v3, v87, v89
	v_mov_b32_e32 v87, v3
	s_nop 1
	v_permlane16_swap_b32_e32 v3, v87
	v_max_f32_e32 v87, v87, v87
	v_max_f32_e32 v3, v3, v3
	v_max_f32_e32 v3, v3, v87
	v_mov_b32_e32 v87, v3
	s_nop 1
	v_permlane32_swap_b32_e32 v3, v87
	v_max3_f32 v3, v188, v3, v87
	v_cmp_neq_f32_e32 vcc, s71, v3
	s_nop 1
	v_cndmask_b32_e32 v87, 0, v3, vcc
	v_sub_f32_e32 v2, v2, v87
	v_sub_f32_e32 v0, v0, v87
	v_exp_f32_e32 v2, v2
	v_exp_f32_e32 v91, v0
	v_sub_f32_e32 v0, v96, v87
	v_sub_f32_e32 v89, v92, v87
	v_exp_f32_e32 v0, v0
	v_exp_f32_e32 v198, v89
	v_add_f32_e32 v199, v91, v2
	v_sub_f32_e32 v92, v93, v87
	v_sub_f32_e32 v89, v97, v87
	v_pk_add_f32 v[200:201], v[198:199], v[0:1]
	v_exp_f32_e32 v199, v92
	v_pk_add_f32 v[200:201], v[200:201], v[200:201] op_sel_hi:[0,1]
	v_sub_f32_e32 v92, v98, v87
	v_exp_f32_e32 v89, v89
	v_exp_f32_e32 v200, v92
	v_sub_f32_e32 v92, v94, v87
	v_exp_f32_e32 v92, v92
	v_add_f32_e32 v93, v199, v89
	v_sub_f32_e32 v94, v95, v87
	v_exp_f32_e32 v204, v94
	v_pk_add_f32 v[96:97], v[92:93], v[200:201]
	v_sub_f32_e32 v93, v99, v87
	v_pk_add_f32 v[96:97], v[96:97], v[96:97] op_sel_hi:[0,1]
	v_exp_f32_e32 v93, v93
	v_sub_f32_e32 v88, v88, v87
	v_sub_f32_e32 v84, v84, v87
	v_exp_f32_e32 v96, v88
	v_exp_f32_e32 v94, v84
	v_cvt_pk_bf16_f32 v88, v2, v0
	v_add_f32_e32 v95, v204, v93
	v_sub_f32_e32 v0, v212, v87
	v_pk_add_f32 v[98:99], v[94:95], v[96:97]
	v_exp_f32_e32 v95, v0
	v_sub_f32_e32 v0, v85, v87
	v_pk_add_f32 v[98:99], v[98:99], v[98:99] op_sel_hi:[0,1]
	v_exp_f32_e32 v97, v0
	v_sub_f32_e32 v0, v90, v87
	v_exp_f32_e32 v98, v0
	v_sub_f32_e32 v0, v86, v87
	v_cvt_pk_bf16_f32 v89, v89, v200
	v_exp_f32_e32 v200, v0
	v_sub_f32_e32 v188, v188, v87
	v_exp_f32_e32 v0, v188
	v_add_f32_e32 v201, v97, v95
	v_pk_add_f32 v[84:85], v[200:201], v[98:99]
	v_cvt_pk_bf16_f32 v90, v91, v198
	v_cvt_pk_bf16_f32 v91, v199, v92
	s_nop 0
	v_add_f32_e32 v2, v84, v85
	v_fmac_f32_e32 v2, v189, v0
	v_cvt_pk_bf16_f32 v84, v93, v96
	v_cvt_pk_bf16_f32 v85, v95, v98
	v_cvt_pk_bf16_f32 v86, v204, v94
	v_cvt_pk_bf16_f32 v87, v97, v200
	v_add_u32_e32 v216, 0x12f00, v190
	ds_read2_b64 v[92:95], v216 offset1:4
	ds_read2_b64 v[96:99], v219 offset0:144 offset1:148
	ds_read2_b64 v[198:201], v234 offset0:176 offset1:180
	ds_read2_b64 v[212:215], v235 offset0:16 offset1:20
	v_pk_mul_f32 v[68:69], v[68:69], v[0:1] op_sel_hi:[1,0]
	v_pk_mul_f32 v[70:71], v[70:71], v[0:1] op_sel_hi:[1,0]
	v_pk_mul_f32 v[80:81], v[80:81], v[0:1] op_sel_hi:[1,0]
	v_pk_mul_f32 v[82:83], v[82:83], v[0:1] op_sel_hi:[1,0]
	v_pk_mul_f32 v[72:73], v[72:73], v[0:1] op_sel_hi:[1,0]
	v_pk_mul_f32 v[74:75], v[74:75], v[0:1] op_sel_hi:[1,0]
	v_pk_mul_f32 v[76:77], v[76:77], v[0:1] op_sel_hi:[1,0]
	v_pk_mul_f32 v[78:79], v[78:79], v[0:1] op_sel_hi:[1,0]
	s_waitcnt lgkmcnt(4)
	v_mfma_f32_16x16x32_bf16 v[68:71], v[220:223], v[88:91], v[68:71]
	v_mfma_f32_16x16x32_bf16 v[80:83], v[224:227], v[88:91], v[80:83]
	v_mfma_f32_16x16x32_bf16 v[72:75], v[248:251], v[88:91], v[72:75]
	ds_read2_b64 v[220:223], v216 offset0:16 offset1:20
	s_waitcnt lgkmcnt(4)
	v_mfma_f32_16x16x32_bf16 v[76:79], v[92:95], v[88:91], v[76:79]
	s_waitcnt lgkmcnt(3)
	v_mfma_f32_16x16x32_bf16 v[68:71], v[96:99], v[84:87], v[68:71]
	s_waitcnt lgkmcnt(2)
	v_mfma_f32_16x16x32_bf16 v[80:83], v[198:201], v[84:87], v[80:83]
	s_waitcnt lgkmcnt(1)
	v_mfma_f32_16x16x32_bf16 v[72:75], v[212:215], v[84:87], v[72:75]
	s_waitcnt lgkmcnt(0)
	v_mfma_f32_16x16x32_bf16 v[76:79], v[220:223], v[84:87], v[76:79]
	s_add_i32 s47, s47, 2
	v_add_u32_e32 v190, 0x100, v190
	v_add_u32_e32 v191, 0x4800, v191
	v_add_u32_e32 v192, 0xf8, v192
	v_add_u32_e32 v193, 0xf8, v193
	v_add_u32_e32 v194, 0xf8, v194
	v_add_u32_e32 v195, 0xf8, v195
	v_add_u32_e32 v206, 0xf8, v206
	v_add_u32_e32 v207, 0xf8, v207
	v_add_u32_e32 v208, 0xf8, v208
	v_add_u32_e32 v209, 0xf8, v209
	v_add_u32_e32 v210, 0x4800, v210
	s_cmp_lt_i32 s47, s46
	v_add_u32_e32 v211, 0x100, v211
	s_cbranch_scc0 .LBB0_810
	v_mov_b32_e32 v188, v3
	v_mov_b32_e32 v189, v2
	s_branch .LBB0_775

; template <int ND> ...
;     ...
;     __builtin_amdgcn_s_setprio(1);
; #pragma unroll
;     for (int kk = 0; kk < 2; ++kk)
; #pragma unroll
;         for (int u = 0; u < 2 * ND; ++u) {
;             const bf16x8 kf = *(const LAS bf16x8*)(lds + kbase + (key0[u >> 1] + (u & 1) * 16 + fr) * 144 + kk * 64 + fq * 16);
;             sc[u] = mfma16(kf, qf[kk], sc[u]); }
;     __builtin_amdgcn_s_setprio(0);
;     if (loc) {
; #pragma unroll
;         for (int g = 0; g < ND; ++g)
; #pragma unroll
;             for (int i = 0; i < 4; ++i) {
;                 const int ck0 = cst + fq * 4 + i, ck1 = ck0 + 16;
;                 const int rel0 = min(max(ck0 - cq + 15, 0), 30), rel1 = min(max(ck1 - cq + 15, 0), 30);
;                 const bool v0 = (ck0 >= c0w) && (ck0 < c0w + 16), v1 = (ck1 >= c0w) && (ck1 < c0w + 16);
;                 sc[2 * g][i] = v0 ? sc[2 * g][i] + rpb[dr[g] * 31 + rel0] : -INFINITY;
;                 sc[2 * g + 1][i] = v1 ? sc[2 * g + 1][i] + rpb[dr[g] * 31 + rel1] : -INFINITY; }
;     }
;     float mx = -INFINITY;
; #pragma unroll
;     for (int u = 0; u < 2 * ND; ++u) mx = fmaxf(mx, fmaxf(fmaxf(sc[u][0], sc[u][1]), fmaxf(sc[u][2], sc[u][3])));
;     mx = xmax16(mx); mx = xmax32(mx);
;     const float m_new = fmaxf(m_run, mx);
;     const float m_use = (m_new == -INFINITY) ? 0.f : m_new;
;     const float alpha = __builtin_amdgcn_exp2f(m_run - m_use);
;     float ps_sum = 0.f; bf16x8 pf[ND];
; #pragma unroll
;     for (int g = 0; g < ND; ++g) { float pv[8];
; #pragma unroll
;         for (int i = 0; i < 4; ++i) { pv[i] = __builtin_amdgcn_exp2f(sc[2 * g][i] - m_use); pv[4 + i] = __builtin_amdgcn_exp2f(sc[2 * g + 1][i] - m_use); ps_sum += pv[i] + pv[4 + i]; }
;         u32x4 pw; pw.x = pk_bf16(pv[0], pv[1]); pw.y = pk_bf16(pv[2], pv[3]); pw.z = pk_bf16(pv[4], pv[5]); pw.w = pk_bf16(pv[6], pv[7]);
;         pf[g] = as_bf8(pw); }
;     l_run = l_run * alpha + ps_sum; m_run = m_new;
;     __builtin_amdgcn_s_setprio(1);
; #pragma unroll
;     for (int d = 0; d < 4; ++d) { O[d] = O[d] * alpha;
; #pragma unroll
;         for (int g = 0; g < ND; ++g) {
;             const u32x2 va = *(const LAS u32x2*)(lds + vbase + (d * 16 + fr) * vstr + (key0[g] + fq * 4) * 2);
;             const u32x2 vb = *(const LAS u32x2*)(lds + vbase + (d * 16 + fr) * vstr + (key0[g] + 16 + fq * 4) * 2);
;             u32x4 vw; vw.x = va.x; vw.y = va.y; vw.z = vb.x; vw.w = vb.y;
.LBB0_811:
	s_sub_i32 s3, s4, s3
	s_lshl_b32 s3, s3, 6
	s_or_b32 s3, s3, s56
	s_add_i32 s46, s82, s4
	s_mulk_i32 s46, 0x7c
	s_add_i32 s46, s46, 0
	s_add_i32 s46, s46, 0x1e400
	v_lshl_add_u32 v219, v147, 2, s46
	v_lshl_add_u32 v220, v146, 2, s46
	v_lshl_add_u32 v221, v149, 2, s46
	v_lshl_add_u32 v222, v148, 2, s46
	v_lshl_add_u32 v223, v151, 2, s46
	v_lshl_add_u32 v224, v150, 2, s46
	v_lshl_add_u32 v225, v153, 2, s46
	v_lshl_add_u32 v226, v152, 2, s46
	ds_read_b32 v219, v219 offset:868
	ds_read_b32 v220, v220 offset:868
	ds_read_b32 v221, v221 offset:868
	ds_read_b32 v222, v222 offset:868
	ds_read_b32 v223, v223 offset:868
	ds_read_b32 v224, v224 offset:868
	ds_read_b32 v225, v225 offset:868
	ds_read_b32 v226, v226 offset:868
	v_add_u32_e32 v0, s3, v107
	v_mad_u64_u32 v[96:97], s[4:5], v0, s55, v[108:109]
	ds_read_b128 v[84:87], v96
	ds_read_b128 v[92:95], v96 offset:64
	ds_read_b128 v[88:91], v96 offset:2304
	s_waitcnt lgkmcnt(2)
	v_mfma_f32_16x16x32_bf16 v[84:87], v[84:87], v[4:7], 0
	s_waitcnt lgkmcnt(1)
	v_mfma_f32_16x16x32_bf16 v[84:87], v[92:95], v[8:11], v[84:87]
	ds_read_b128 v[92:95], v96 offset:2368
	s_waitcnt lgkmcnt(1)
	v_mfma_f32_16x16x32_bf16 v[88:91], v[88:91], v[4:7], 0
	s_waitcnt lgkmcnt(0)
	v_mfma_f32_16x16x32_bf16 v[88:91], v[92:95], v[8:11], v[88:91]
	v_mov_b32_e32 v227, 0xff800000
	s_waitcnt lgkmcnt(0)
	s_nop 4
	v_add_f32_e32 v219, v84, v219
	v_cndmask_b32_e64 v92, v227, v219, s[64:65]
	v_add_f32_e32 v220, v88, v220
	v_cndmask_b32_e64 v0, v227, v220, s[90:91]
	v_add_f32_e32 v221, v85, v221
	v_cndmask_b32_e64 v88, v227, v221, s[74:75]
	v_add_f32_e32 v222, v89, v222
	v_cndmask_b32_e64 v84, v227, v222, s[96:97]
	v_add_f32_e32 v223, v86, v223
	v_cndmask_b32_e64 v89, v227, v223, s[8:9]
	v_add_f32_e32 v224, v90, v224
	v_cndmask_b32_e64 v85, v227, v224, s[86:87]
	v_add_f32_e32 v225, v87, v225
	v_cndmask_b32_e64 v90, v227, v225, s[60:61]
	v_add_f32_e32 v226, v91, v226
	v_cndmask_b32_e64 v86, v227, v226, s[52:53]
	v_add_lshl_u32 v234, s3, v106, 1
	v_add_u32_e32 v235, v157, v234
	v_add_u32_e32 v234, v156, v234
	ds_read_b64 v[220:221], v234 offset:46080
	ds_read_b64 v[222:223], v234 offset:46112
	ds_read_b64 v[224:225], v234 offset:56576
	ds_read_b64 v[226:227], v234 offset:56608
	ds_read_b64 v[248:249], v235 offset:20992
	ds_read_b64 v[250:251], v235 offset:21024
	v_max_f32_e32 v87, v90, v90
	v_max_f32_e32 v91, v89, v89
	v_max_f32_e32 v87, v91, v87
	v_max_f32_e32 v91, v86, v86
	v_max_f32_e32 v93, v85, v85
	v_max_f32_e32 v91, v93, v91
	v_max3_f32 v87, v92, v88, v87
	v_max3_f32 v91, v0, v84, v91
	v_max3_f32 v87, v87, s71, v91
	v_mov_b32_e32 v91, v87
	s_nop 1
	v_permlane16_swap_b32_e32 v87, v91
	v_max_f32_e32 v91, v91, v91
	v_max_f32_e32 v87, v87, v87
	v_max_f32_e32 v87, v87, v91
	v_mov_b32_e32 v91, v87
	s_nop 1
	v_permlane32_swap_b32_e32 v87, v91
	v_max3_f32 v97, v3, v87, v91
	v_cmp_neq_f32_e32 vcc, s71, v97
	s_nop 1
	v_cndmask_b32_e32 v87, 0, v97, vcc
	v_sub_f32_e32 v91, v92, v87
	v_sub_f32_e32 v0, v0, v87
	v_exp_f32_e32 v91, v91
	v_exp_f32_e32 v98, v0
	v_sub_f32_e32 v0, v88, v87
	v_sub_f32_e32 v84, v84, v87
	v_exp_f32_e32 v0, v0
	v_exp_f32_e32 v92, v84
	v_add_f32_e32 v93, v98, v91
	v_sub_f32_e32 v84, v89, v87
	v_sub_f32_e32 v3, v3, v87
	v_pk_add_f32 v[94:95], v[92:93], v[0:1]
	v_exp_f32_e32 v93, v84
	v_sub_f32_e32 v84, v85, v87
	v_pk_add_f32 v[94:95], v[94:95], v[94:95] op_sel_hi:[0,1]
	v_exp_f32_e32 v99, v84
	v_sub_f32_e32 v84, v90, v87
	v_exp_f32_e32 v94, v84
	v_sub_f32_e32 v84, v86, v87
	v_exp_f32_e32 v88, v84
	v_exp_f32_e32 v96, v3
	v_add_f32_e32 v89, v99, v93
	v_pk_add_f32 v[84:85], v[88:89], v[94:95]
	s_nop 0
	v_add_f32_e32 v95, v84, v85
	v_cvt_pk_bf16_f32 v84, v91, v0
	v_cvt_pk_bf16_f32 v85, v93, v94
	v_cvt_pk_bf16_f32 v86, v98, v92
	v_cvt_pk_bf16_f32 v87, v99, v88
	v_fmac_f32_e32 v95, v2, v96
	ds_read_b64 v[88:89], v235 offset:31488
	ds_read_b64 v[90:91], v235 offset:31520
	v_pk_mul_f32 v[68:69], v[68:69], v[96:97] op_sel_hi:[1,0]
	v_pk_mul_f32 v[70:71], v[70:71], v[96:97] op_sel_hi:[1,0]
	v_pk_mul_f32 v[80:81], v[80:81], v[96:97] op_sel_hi:[1,0]
	v_pk_mul_f32 v[82:83], v[82:83], v[96:97] op_sel_hi:[1,0]
	v_pk_mul_f32 v[72:73], v[72:73], v[96:97] op_sel_hi:[1,0]
	v_pk_mul_f32 v[74:75], v[74:75], v[96:97] op_sel_hi:[1,0]
	v_pk_mul_f32 v[76:77], v[76:77], v[96:97] op_sel_hi:[1,0]
	v_pk_mul_f32 v[78:79], v[78:79], v[96:97] op_sel_hi:[1,0]
	s_waitcnt lgkmcnt(2)
	v_mfma_f32_16x16x32_bf16 v[68:71], v[220:223], v[84:87], v[68:71]
	v_mfma_f32_16x16x32_bf16 v[80:83], v[224:227], v[84:87], v[80:83]
	v_mfma_f32_16x16x32_bf16 v[72:75], v[248:251], v[84:87], v[72:75]
	s_waitcnt lgkmcnt(0)
	v_mfma_f32_16x16x32_bf16 v[76:79], v[88:91], v[84:87], v[76:79]
	v_mov_b32_e32 v3, v97
	v_mov_b32_e32 v2, v95
	s_branch .LBB0_737
